# per-block K-rotation (k0=(bid>>3)&15) of the DMA k-loop in ffn_in to spread L2 channel pressure
# speedup vs baseline: 1.0053x; 1.0052x over previous
.Lf8_tile:
	s_cmp_lt_u32 s15, 0xb00
	s_cbranch_scc0 .Lf8_end
	s_and_b32 s2, s15, 63
	s_lshr_b32 s3, s15, 6
	s_lshl_b32 s14, s2, 18
	s_add_u32 s8, s26, s14
	s_addc_u32 s9, s27, 0
	s_lshl_b32 s14, s3, 18
	s_add_u32 s10, s28, s14
	s_addc_u32 s11, s29, 0
	s_mul_i32 s14, s2, 0xb0000
	s_lshl_b32 s6, s3, 7
	s_add_u32 s14, s14, s6
	s_add_u32 s20, s4, 0x9b7a100
	s_addc_u32 s21, s5, 0
	s_add_u32 s20, s20, s14
	s_addc_u32 s21, s21, 0
	v_readfirstlane_b32 s12, v247
	s_nop 3
	s_lshl_b32 s12, s12, 12
	s_lshr_b32 s22, s58, 3
	s_and_b32 s22, s22, 15
	s_sub_u32 s23, 16, s22
	s_lshl_b32 s22, s22, 7
	s_add_u32 s8, s8, s22
	s_addc_u32 s9, s9, 0
	s_add_u32 s10, s10, s22
	s_addc_u32 s11, s11, 0
	s_add_u32 m0, s12, 0x0
	v_mov_b32_e32 v0, 0
	global_load_lds_dwordx4 v248, s[8:9]
	v_mov_b32_e32 v1, 0
	s_add_u32 m0, s12, 0x400
	v_mov_b32_e32 v2, 0
	global_load_lds_dwordx4 v249, s[8:9]
	v_mov_b32_e32 v3, 0
	s_add_u32 m0, s12, 0x800
	v_mov_b32_e32 v4, 0
	global_load_lds_dwordx4 v250, s[8:9]
	v_mov_b32_e32 v5, 0
	s_add_u32 m0, s12, 0xc00
	v_mov_b32_e32 v6, 0
	global_load_lds_dwordx4 v251, s[8:9]
	v_mov_b32_e32 v7, 0
	s_add_u32 m0, s12, 0x8000
	v_mov_b32_e32 v8, 0
	global_load_lds_dwordx4 v248, s[10:11] sc1
	v_mov_b32_e32 v9, 0
	s_add_u32 m0, s12, 0x8400
	v_mov_b32_e32 v10, 0
	global_load_lds_dwordx4 v249, s[10:11] sc1
	v_mov_b32_e32 v11, 0
	s_add_u32 m0, s12, 0x8800
	v_mov_b32_e32 v12, 0
	global_load_lds_dwordx4 v250, s[10:11] sc1
	v_mov_b32_e32 v13, 0
	s_add_u32 m0, s12, 0x8c00
	v_mov_b32_e32 v14, 0
	global_load_lds_dwordx4 v251, s[10:11] sc1
	v_mov_b32_e32 v15, 0
	s_sub_u32 s23, s23, 1
	s_mov_b32 s14, 0x80
	s_cmp_eq_u32 s23, 0
	s_cselect_b32 s14, 0xfffff880, s14
	s_cselect_b32 s24, -1, 0
	s_add_u32 s8, s8, s14
	s_addc_u32 s9, s9, s24
	s_add_u32 s10, s10, s14
	s_addc_u32 s11, s11, s24
	s_add_u32 m0, s12, 0x4000
	v_mov_b32_e32 v16, 0
	global_load_lds_dwordx4 v248, s[8:9]
	v_mov_b32_e32 v17, 0
	s_add_u32 m0, s12, 0x4400
	v_mov_b32_e32 v18, 0
	global_load_lds_dwordx4 v249, s[8:9]
	v_mov_b32_e32 v19, 0
	s_add_u32 m0, s12, 0x4800
	v_mov_b32_e32 v20, 0
	global_load_lds_dwordx4 v250, s[8:9]
	v_mov_b32_e32 v21, 0
	s_add_u32 m0, s12, 0x4c00
	v_mov_b32_e32 v22, 0
	global_load_lds_dwordx4 v251, s[8:9]
	v_mov_b32_e32 v23, 0
	s_add_u32 m0, s12, 0xc000
	v_mov_b32_e32 v24, 0
	global_load_lds_dwordx4 v248, s[10:11] sc1
	v_mov_b32_e32 v25, 0
	s_add_u32 m0, s12, 0xc400
	v_mov_b32_e32 v26, 0
	global_load_lds_dwordx4 v249, s[10:11] sc1
	v_mov_b32_e32 v27, 0
	s_add_u32 m0, s12, 0xc800
	v_mov_b32_e32 v28, 0
	global_load_lds_dwordx4 v250, s[10:11] sc1
	v_mov_b32_e32 v29, 0
	s_add_u32 m0, s12, 0xcc00
	v_mov_b32_e32 v30, 0
	global_load_lds_dwordx4 v251, s[10:11] sc1
	v_mov_b32_e32 v31, 0
	s_sub_u32 s23, s23, 1
	s_mov_b32 s14, 0x80
	s_cmp_eq_u32 s23, 0
	s_cselect_b32 s14, 0xfffff880, s14
	s_cselect_b32 s24, -1, 0
	s_add_u32 s8, s8, s14
	s_addc_u32 s9, s9, s24
	s_add_u32 s10, s10, s14
	s_addc_u32 s11, s11, s24
	v_mov_b32_e32 v32, 0
	v_mov_b32_e32 v33, 0
	v_mov_b32_e32 v34, 0
	v_mov_b32_e32 v35, 0
	v_mov_b32_e32 v36, 0
	v_mov_b32_e32 v37, 0
	v_mov_b32_e32 v38, 0
	v_mov_b32_e32 v39, 0
	v_mov_b32_e32 v40, 0
	v_mov_b32_e32 v41, 0
	v_mov_b32_e32 v42, 0
	v_mov_b32_e32 v43, 0
	v_mov_b32_e32 v44, 0
	v_mov_b32_e32 v45, 0
	v_mov_b32_e32 v46, 0
	v_mov_b32_e32 v47, 0
	v_mov_b32_e32 v48, 0
	v_mov_b32_e32 v49, 0
	v_mov_b32_e32 v50, 0
	v_mov_b32_e32 v51, 0
	v_mov_b32_e32 v52, 0
	v_mov_b32_e32 v53, 0
	v_mov_b32_e32 v54, 0
	v_mov_b32_e32 v55, 0
	v_mov_b32_e32 v56, 0
	v_mov_b32_e32 v57, 0
	v_mov_b32_e32 v58, 0
	v_mov_b32_e32 v59, 0
	v_mov_b32_e32 v60, 0
	v_mov_b32_e32 v61, 0
	v_mov_b32_e32 v62, 0
	v_mov_b32_e32 v63, 0
	s_waitcnt vmcnt(8)
	s_barrier
	ds_read_b128 v[64:67], v252 offset:0
	ds_read_b128 v[96:99], v254 offset:32768
	ds_read_b128 v[100:103], v254 offset:34816
	ds_read_b128 v[104:107], v254 offset:36864
	ds_read_b128 v[108:111], v254 offset:38912
	ds_read_b128 v[68:71], v252 offset:2048
	ds_read_b128 v[72:75], v252 offset:4096
	ds_read_b128 v[76:79], v252 offset:6144
	ds_read_b128 v[80:83], v253 offset:0
	ds_read_b128 v[112:115], v255 offset:32768
	ds_read_b128 v[116:119], v255 offset:34816
	ds_read_b128 v[120:123], v255 offset:36864
	ds_read_b128 v[124:127], v255 offset:38912
	s_waitcnt lgkmcnt(11)
	v_mfma_f32_16x16x32_bf16 v[0:3], v[96:99], v[64:67], v[0:3]
	s_waitcnt lgkmcnt(10)
	v_mfma_f32_16x16x32_bf16 v[4:7], v[100:103], v[64:67], v[4:7]
	s_waitcnt lgkmcnt(9)
	v_mfma_f32_16x16x32_bf16 v[8:11], v[104:107], v[64:67], v[8:11]
	s_waitcnt lgkmcnt(8)
	v_mfma_f32_16x16x32_bf16 v[12:15], v[108:111], v[64:67], v[12:15]
	ds_read_b128 v[84:87], v253 offset:2048
	ds_read_b128 v[88:91], v253 offset:4096
	ds_read_b128 v[92:95], v253 offset:6144
	s_waitcnt lgkmcnt(10)
	v_mfma_f32_16x16x32_bf16 v[16:19], v[96:99], v[68:71], v[16:19]
	v_mfma_f32_16x16x32_bf16 v[20:23], v[100:103], v[68:71], v[20:23]
	v_mfma_f32_16x16x32_bf16 v[24:27], v[104:107], v[68:71], v[24:27]
	v_mfma_f32_16x16x32_bf16 v[28:31], v[108:111], v[68:71], v[28:31]
	s_waitcnt lgkmcnt(0)
	s_barrier
	s_add_u32 m0, s12, 0x0
	v_mfma_f32_16x16x32_bf16 v[32:35], v[96:99], v[72:75], v[32:35]
	global_load_lds_dwordx4 v248, s[8:9]
	s_add_u32 m0, s12, 0x400
	v_mfma_f32_16x16x32_bf16 v[36:39], v[100:103], v[72:75], v[36:39]
	global_load_lds_dwordx4 v249, s[8:9]
	s_add_u32 m0, s12, 0x800
	v_mfma_f32_16x16x32_bf16 v[40:43], v[104:107], v[72:75], v[40:43]
	global_load_lds_dwordx4 v250, s[8:9]
	s_add_u32 m0, s12, 0xc00
	v_mfma_f32_16x16x32_bf16 v[44:47], v[108:111], v[72:75], v[44:47]
	global_load_lds_dwordx4 v251, s[8:9]
	s_add_u32 m0, s12, 0x8000
	v_mfma_f32_16x16x32_bf16 v[48:51], v[96:99], v[76:79], v[48:51]
	global_load_lds_dwordx4 v248, s[10:11] sc1
	s_add_u32 m0, s12, 0x8400
	v_mfma_f32_16x16x32_bf16 v[52:55], v[100:103], v[76:79], v[52:55]
	global_load_lds_dwordx4 v249, s[10:11] sc1
	s_add_u32 m0, s12, 0x8800
	v_mfma_f32_16x16x32_bf16 v[56:59], v[104:107], v[76:79], v[56:59]
	global_load_lds_dwordx4 v250, s[10:11] sc1
	s_add_u32 m0, s12, 0x8c00
	v_mfma_f32_16x16x32_bf16 v[60:63], v[108:111], v[76:79], v[60:63]
	global_load_lds_dwordx4 v251, s[10:11] sc1
	s_sub_u32 s23, s23, 1
	s_mov_b32 s14, 0x80
	s_cmp_eq_u32 s23, 0
	s_cselect_b32 s14, 0xfffff880, s14
	s_cselect_b32 s24, -1, 0
	s_add_u32 s8, s8, s14
	s_addc_u32 s9, s9, s24
	s_add_u32 s10, s10, s14
	s_addc_u32 s11, s11, s24
	s_waitcnt vmcnt(8)
	s_barrier
	ds_read_b128 v[64:67], v252 offset:16384
	ds_read_b128 v[96:99], v254 offset:49152
	ds_read_b128 v[100:103], v254 offset:51200
	ds_read_b128 v[104:107], v254 offset:53248
	ds_read_b128 v[108:111], v254 offset:55296
	ds_read_b128 v[68:71], v252 offset:18432
	ds_read_b128 v[72:75], v252 offset:20480
	ds_read_b128 v[76:79], v252 offset:22528
	v_mfma_f32_16x16x32_bf16 v[0:3], v[112:115], v[80:83], v[0:3]
	v_mfma_f32_16x16x32_bf16 v[4:7], v[116:119], v[80:83], v[4:7]
	v_mfma_f32_16x16x32_bf16 v[8:11], v[120:123], v[80:83], v[8:11]
	v_mfma_f32_16x16x32_bf16 v[12:15], v[124:127], v[80:83], v[12:15]
	v_mfma_f32_16x16x32_bf16 v[16:19], v[112:115], v[84:87], v[16:19]
	v_mfma_f32_16x16x32_bf16 v[20:23], v[116:119], v[84:87], v[20:23]
	v_mfma_f32_16x16x32_bf16 v[24:27], v[120:123], v[84:87], v[24:27]
	v_mfma_f32_16x16x32_bf16 v[28:31], v[124:127], v[84:87], v[28:31]
	v_mfma_f32_16x16x32_bf16 v[32:35], v[112:115], v[88:91], v[32:35]
	v_mfma_f32_16x16x32_bf16 v[36:39], v[116:119], v[88:91], v[36:39]
	v_mfma_f32_16x16x32_bf16 v[40:43], v[120:123], v[88:91], v[40:43]
	v_mfma_f32_16x16x32_bf16 v[44:47], v[124:127], v[88:91], v[44:47]
	v_mfma_f32_16x16x32_bf16 v[48:51], v[112:115], v[92:95], v[48:51]
	v_mfma_f32_16x16x32_bf16 v[52:55], v[116:119], v[92:95], v[52:55]
	v_mfma_f32_16x16x32_bf16 v[56:59], v[120:123], v[92:95], v[56:59]
	v_mfma_f32_16x16x32_bf16 v[60:63], v[124:127], v[92:95], v[60:63]
	ds_read_b128 v[80:83], v253 offset:16384
	ds_read_b128 v[112:115], v255 offset:49152
	ds_read_b128 v[116:119], v255 offset:51200
	ds_read_b128 v[120:123], v255 offset:53248
	ds_read_b128 v[124:127], v255 offset:55296
	ds_read_b128 v[84:87], v253 offset:18432
	ds_read_b128 v[88:91], v253 offset:20480
	ds_read_b128 v[92:95], v253 offset:22528
	s_waitcnt lgkmcnt(14)
	v_mfma_f32_16x16x32_bf16 v[0:3], v[96:99], v[64:67], v[0:3]
	s_waitcnt lgkmcnt(13)
	v_mfma_f32_16x16x32_bf16 v[4:7], v[100:103], v[64:67], v[4:7]
	s_waitcnt lgkmcnt(12)
	v_mfma_f32_16x16x32_bf16 v[8:11], v[104:107], v[64:67], v[8:11]
	s_waitcnt lgkmcnt(11)
	v_mfma_f32_16x16x32_bf16 v[12:15], v[108:111], v[64:67], v[12:15]
	s_waitcnt lgkmcnt(10)
	v_mfma_f32_16x16x32_bf16 v[16:19], v[96:99], v[68:71], v[16:19]
	v_mfma_f32_16x16x32_bf16 v[20:23], v[100:103], v[68:71], v[20:23]
	v_mfma_f32_16x16x32_bf16 v[24:27], v[104:107], v[68:71], v[24:27]
	v_mfma_f32_16x16x32_bf16 v[28:31], v[108:111], v[68:71], v[28:31]
	s_waitcnt lgkmcnt(0)
	s_barrier
	s_add_u32 m0, s12, 0x4000
	v_mfma_f32_16x16x32_bf16 v[32:35], v[96:99], v[72:75], v[32:35]
	global_load_lds_dwordx4 v248, s[8:9]
	s_add_u32 m0, s12, 0x4400
	v_mfma_f32_16x16x32_bf16 v[36:39], v[100:103], v[72:75], v[36:39]
	global_load_lds_dwordx4 v249, s[8:9]
	s_add_u32 m0, s12, 0x4800
	v_mfma_f32_16x16x32_bf16 v[40:43], v[104:107], v[72:75], v[40:43]
	global_load_lds_dwordx4 v250, s[8:9]
	s_add_u32 m0, s12, 0x4c00
	v_mfma_f32_16x16x32_bf16 v[44:47], v[108:111], v[72:75], v[44:47]
	global_load_lds_dwordx4 v251, s[8:9]
	s_add_u32 m0, s12, 0xc000
	v_mfma_f32_16x16x32_bf16 v[48:51], v[96:99], v[76:79], v[48:51]
	global_load_lds_dwordx4 v248, s[10:11] sc1
	s_add_u32 m0, s12, 0xc400
	v_mfma_f32_16x16x32_bf16 v[52:55], v[100:103], v[76:79], v[52:55]
	global_load_lds_dwordx4 v249, s[10:11] sc1
	s_add_u32 m0, s12, 0xc800
	v_mfma_f32_16x16x32_bf16 v[56:59], v[104:107], v[76:79], v[56:59]
	global_load_lds_dwordx4 v250, s[10:11] sc1
	s_add_u32 m0, s12, 0xcc00
	v_mfma_f32_16x16x32_bf16 v[60:63], v[108:111], v[76:79], v[60:63]
	global_load_lds_dwordx4 v251, s[10:11] sc1
	s_sub_u32 s23, s23, 1
	s_mov_b32 s14, 0x80
	s_cmp_eq_u32 s23, 0
	s_cselect_b32 s14, 0xfffff880, s14
	s_cselect_b32 s24, -1, 0
	s_add_u32 s8, s8, s14
	s_addc_u32 s9, s9, s24
	s_add_u32 s10, s10, s14
	s_addc_u32 s11, s11, s24
	s_mov_b32 s13, 6
.Lf8_loop:
	s_waitcnt vmcnt(8)
	s_barrier
	ds_read_b128 v[64:67], v252 offset:0
	ds_read_b128 v[96:99], v254 offset:32768
	ds_read_b128 v[100:103], v254 offset:34816
	ds_read_b128 v[104:107], v254 offset:36864
	ds_read_b128 v[108:111], v254 offset:38912
	ds_read_b128 v[68:71], v252 offset:2048
	ds_read_b128 v[72:75], v252 offset:4096
	ds_read_b128 v[76:79], v252 offset:6144
	v_mfma_f32_16x16x32_bf16 v[0:3], v[112:115], v[80:83], v[0:3]
	v_mfma_f32_16x16x32_bf16 v[4:7], v[116:119], v[80:83], v[4:7]
	v_mfma_f32_16x16x32_bf16 v[8:11], v[120:123], v[80:83], v[8:11]
	v_mfma_f32_16x16x32_bf16 v[12:15], v[124:127], v[80:83], v[12:15]
	v_mfma_f32_16x16x32_bf16 v[16:19], v[112:115], v[84:87], v[16:19]
	v_mfma_f32_16x16x32_bf16 v[20:23], v[116:119], v[84:87], v[20:23]
	v_mfma_f32_16x16x32_bf16 v[24:27], v[120:123], v[84:87], v[24:27]
	v_mfma_f32_16x16x32_bf16 v[28:31], v[124:127], v[84:87], v[28:31]
	v_mfma_f32_16x16x32_bf16 v[32:35], v[112:115], v[88:91], v[32:35]
	v_mfma_f32_16x16x32_bf16 v[36:39], v[116:119], v[88:91], v[36:39]
	v_mfma_f32_16x16x32_bf16 v[40:43], v[120:123], v[88:91], v[40:43]
	v_mfma_f32_16x16x32_bf16 v[44:47], v[124:127], v[88:91], v[44:47]
	v_mfma_f32_16x16x32_bf16 v[48:51], v[112:115], v[92:95], v[48:51]
	v_mfma_f32_16x16x32_bf16 v[52:55], v[116:119], v[92:95], v[52:55]
	v_mfma_f32_16x16x32_bf16 v[56:59], v[120:123], v[92:95], v[56:59]
	v_mfma_f32_16x16x32_bf16 v[60:63], v[124:127], v[92:95], v[60:63]
	ds_read_b128 v[80:83], v253 offset:0
	ds_read_b128 v[112:115], v255 offset:32768
	ds_read_b128 v[116:119], v255 offset:34816
	ds_read_b128 v[120:123], v255 offset:36864
	ds_read_b128 v[124:127], v255 offset:38912
	ds_read_b128 v[84:87], v253 offset:2048
	ds_read_b128 v[88:91], v253 offset:4096
	ds_read_b128 v[92:95], v253 offset:6144
	s_waitcnt lgkmcnt(14)
	v_mfma_f32_16x16x32_bf16 v[0:3], v[96:99], v[64:67], v[0:3]
	s_waitcnt lgkmcnt(13)
	v_mfma_f32_16x16x32_bf16 v[4:7], v[100:103], v[64:67], v[4:7]
	s_waitcnt lgkmcnt(12)
	v_mfma_f32_16x16x32_bf16 v[8:11], v[104:107], v[64:67], v[8:11]
	s_waitcnt lgkmcnt(11)
	v_mfma_f32_16x16x32_bf16 v[12:15], v[108:111], v[64:67], v[12:15]
	s_waitcnt lgkmcnt(10)
	v_mfma_f32_16x16x32_bf16 v[16:19], v[96:99], v[68:71], v[16:19]
	v_mfma_f32_16x16x32_bf16 v[20:23], v[100:103], v[68:71], v[20:23]
	v_mfma_f32_16x16x32_bf16 v[24:27], v[104:107], v[68:71], v[24:27]
	v_mfma_f32_16x16x32_bf16 v[28:31], v[108:111], v[68:71], v[28:31]
	s_waitcnt lgkmcnt(0)
	s_barrier
	s_add_u32 m0, s12, 0x0
	v_mfma_f32_16x16x32_bf16 v[32:35], v[96:99], v[72:75], v[32:35]
	global_load_lds_dwordx4 v248, s[8:9]
	s_add_u32 m0, s12, 0x400
	v_mfma_f32_16x16x32_bf16 v[36:39], v[100:103], v[72:75], v[36:39]
	global_load_lds_dwordx4 v249, s[8:9]
	s_add_u32 m0, s12, 0x800
	v_mfma_f32_16x16x32_bf16 v[40:43], v[104:107], v[72:75], v[40:43]
	global_load_lds_dwordx4 v250, s[8:9]
	s_add_u32 m0, s12, 0xc00
	v_mfma_f32_16x16x32_bf16 v[44:47], v[108:111], v[72:75], v[44:47]
	global_load_lds_dwordx4 v251, s[8:9]
	s_add_u32 m0, s12, 0x8000
	v_mfma_f32_16x16x32_bf16 v[48:51], v[96:99], v[76:79], v[48:51]
	global_load_lds_dwordx4 v248, s[10:11] sc1
	s_add_u32 m0, s12, 0x8400
	v_mfma_f32_16x16x32_bf16 v[52:55], v[100:103], v[76:79], v[52:55]
	global_load_lds_dwordx4 v249, s[10:11] sc1
	s_add_u32 m0, s12, 0x8800
	v_mfma_f32_16x16x32_bf16 v[56:59], v[104:107], v[76:79], v[56:59]
	global_load_lds_dwordx4 v250, s[10:11] sc1
	s_add_u32 m0, s12, 0x8c00
	v_mfma_f32_16x16x32_bf16 v[60:63], v[108:111], v[76:79], v[60:63]
	global_load_lds_dwordx4 v251, s[10:11] sc1
	s_sub_u32 s23, s23, 1
	s_mov_b32 s14, 0x80
	s_cmp_eq_u32 s23, 0
	s_cselect_b32 s14, 0xfffff880, s14
	s_cselect_b32 s24, -1, 0
	s_add_u32 s8, s8, s14
	s_addc_u32 s9, s9, s24
	s_add_u32 s10, s10, s14
	s_addc_u32 s11, s11, s24
	s_waitcnt vmcnt(8)
	s_barrier
	ds_read_b128 v[64:67], v252 offset:16384
	ds_read_b128 v[96:99], v254 offset:49152
	ds_read_b128 v[100:103], v254 offset:51200
	ds_read_b128 v[104:107], v254 offset:53248
	ds_read_b128 v[108:111], v254 offset:55296
	ds_read_b128 v[68:71], v252 offset:18432
	ds_read_b128 v[72:75], v252 offset:20480
	ds_read_b128 v[76:79], v252 offset:22528
	v_mfma_f32_16x16x32_bf16 v[0:3], v[112:115], v[80:83], v[0:3]
	v_mfma_f32_16x16x32_bf16 v[4:7], v[116:119], v[80:83], v[4:7]
	v_mfma_f32_16x16x32_bf16 v[8:11], v[120:123], v[80:83], v[8:11]
	v_mfma_f32_16x16x32_bf16 v[12:15], v[124:127], v[80:83], v[12:15]
	v_mfma_f32_16x16x32_bf16 v[16:19], v[112:115], v[84:87], v[16:19]
	v_mfma_f32_16x16x32_bf16 v[20:23], v[116:119], v[84:87], v[20:23]
	v_mfma_f32_16x16x32_bf16 v[24:27], v[120:123], v[84:87], v[24:27]
	v_mfma_f32_16x16x32_bf16 v[28:31], v[124:127], v[84:87], v[28:31]
	v_mfma_f32_16x16x32_bf16 v[32:35], v[112:115], v[88:91], v[32:35]
	v_mfma_f32_16x16x32_bf16 v[36:39], v[116:119], v[88:91], v[36:39]
	v_mfma_f32_16x16x32_bf16 v[40:43], v[120:123], v[88:91], v[40:43]
	v_mfma_f32_16x16x32_bf16 v[44:47], v[124:127], v[88:91], v[44:47]
	v_mfma_f32_16x16x32_bf16 v[48:51], v[112:115], v[92:95], v[48:51]
	v_mfma_f32_16x16x32_bf16 v[52:55], v[116:119], v[92:95], v[52:55]
	v_mfma_f32_16x16x32_bf16 v[56:59], v[120:123], v[92:95], v[56:59]
	v_mfma_f32_16x16x32_bf16 v[60:63], v[124:127], v[92:95], v[60:63]
	ds_read_b128 v[80:83], v253 offset:16384
	ds_read_b128 v[112:115], v255 offset:49152
	ds_read_b128 v[116:119], v255 offset:51200
	ds_read_b128 v[120:123], v255 offset:53248
	ds_read_b128 v[124:127], v255 offset:55296
	ds_read_b128 v[84:87], v253 offset:18432
	ds_read_b128 v[88:91], v253 offset:20480
	ds_read_b128 v[92:95], v253 offset:22528
	s_waitcnt lgkmcnt(14)
	v_mfma_f32_16x16x32_bf16 v[0:3], v[96:99], v[64:67], v[0:3]
	s_waitcnt lgkmcnt(13)
	v_mfma_f32_16x16x32_bf16 v[4:7], v[100:103], v[64:67], v[4:7]
	s_waitcnt lgkmcnt(12)
	v_mfma_f32_16x16x32_bf16 v[8:11], v[104:107], v[64:67], v[8:11]
	s_waitcnt lgkmcnt(11)
	v_mfma_f32_16x16x32_bf16 v[12:15], v[108:111], v[64:67], v[12:15]
	s_waitcnt lgkmcnt(10)
	v_mfma_f32_16x16x32_bf16 v[16:19], v[96:99], v[68:71], v[16:19]
	v_mfma_f32_16x16x32_bf16 v[20:23], v[100:103], v[68:71], v[20:23]
	v_mfma_f32_16x16x32_bf16 v[24:27], v[104:107], v[68:71], v[24:27]
	v_mfma_f32_16x16x32_bf16 v[28:31], v[108:111], v[68:71], v[28:31]
	s_waitcnt lgkmcnt(0)
	s_barrier
	s_add_u32 m0, s12, 0x4000
	v_mfma_f32_16x16x32_bf16 v[32:35], v[96:99], v[72:75], v[32:35]
	global_load_lds_dwordx4 v248, s[8:9]
	s_add_u32 m0, s12, 0x4400
	v_mfma_f32_16x16x32_bf16 v[36:39], v[100:103], v[72:75], v[36:39]
	global_load_lds_dwordx4 v249, s[8:9]
	s_add_u32 m0, s12, 0x4800
	v_mfma_f32_16x16x32_bf16 v[40:43], v[104:107], v[72:75], v[40:43]
	global_load_lds_dwordx4 v250, s[8:9]
	s_add_u32 m0, s12, 0x4c00
	v_mfma_f32_16x16x32_bf16 v[44:47], v[108:111], v[72:75], v[44:47]
	global_load_lds_dwordx4 v251, s[8:9]
	s_add_u32 m0, s12, 0xc000
	v_mfma_f32_16x16x32_bf16 v[48:51], v[96:99], v[76:79], v[48:51]
	global_load_lds_dwordx4 v248, s[10:11] sc1
	s_add_u32 m0, s12, 0xc400
	v_mfma_f32_16x16x32_bf16 v[52:55], v[100:103], v[76:79], v[52:55]
	global_load_lds_dwordx4 v249, s[10:11] sc1
	s_add_u32 m0, s12, 0xc800
	v_mfma_f32_16x16x32_bf16 v[56:59], v[104:107], v[76:79], v[56:59]
	global_load_lds_dwordx4 v250, s[10:11] sc1
	s_add_u32 m0, s12, 0xcc00
	v_mfma_f32_16x16x32_bf16 v[60:63], v[108:111], v[76:79], v[60:63]
	global_load_lds_dwordx4 v251, s[10:11] sc1
	s_sub_u32 s23, s23, 1
	s_mov_b32 s14, 0x80
	s_cmp_eq_u32 s23, 0
	s_cselect_b32 s14, 0xfffff880, s14
	s_cselect_b32 s24, -1, 0
	s_add_u32 s8, s8, s14
	s_addc_u32 s9, s9, s24
	s_add_u32 s10, s10, s14
	s_addc_u32 s11, s11, s24
	s_sub_u32 s13, s13, 1
	s_cmp_lg_u32 s13, 0
	s_cbranch_scc1 .Lf8_loop
	s_waitcnt vmcnt(8)
	s_barrier
	ds_read_b128 v[64:67], v252 offset:0
	ds_read_b128 v[96:99], v254 offset:32768
	ds_read_b128 v[100:103], v254 offset:34816
	ds_read_b128 v[104:107], v254 offset:36864
	ds_read_b128 v[108:111], v254 offset:38912
	ds_read_b128 v[68:71], v252 offset:2048
	ds_read_b128 v[72:75], v252 offset:4096
	ds_read_b128 v[76:79], v252 offset:6144
	v_mfma_f32_16x16x32_bf16 v[0:3], v[112:115], v[80:83], v[0:3]
	v_mfma_f32_16x16x32_bf16 v[4:7], v[116:119], v[80:83], v[4:7]
	v_mfma_f32_16x16x32_bf16 v[8:11], v[120:123], v[80:83], v[8:11]
	v_mfma_f32_16x16x32_bf16 v[12:15], v[124:127], v[80:83], v[12:15]
	v_mfma_f32_16x16x32_bf16 v[16:19], v[112:115], v[84:87], v[16:19]
	v_mfma_f32_16x16x32_bf16 v[20:23], v[116:119], v[84:87], v[20:23]
	v_mfma_f32_16x16x32_bf16 v[24:27], v[120:123], v[84:87], v[24:27]
	v_mfma_f32_16x16x32_bf16 v[28:31], v[124:127], v[84:87], v[28:31]
	v_mfma_f32_16x16x32_bf16 v[32:35], v[112:115], v[88:91], v[32:35]
	v_mfma_f32_16x16x32_bf16 v[36:39], v[116:119], v[88:91], v[36:39]
	v_mfma_f32_16x16x32_bf16 v[40:43], v[120:123], v[88:91], v[40:43]
	v_mfma_f32_16x16x32_bf16 v[44:47], v[124:127], v[88:91], v[44:47]
	v_mfma_f32_16x16x32_bf16 v[48:51], v[112:115], v[92:95], v[48:51]
	v_mfma_f32_16x16x32_bf16 v[52:55], v[116:119], v[92:95], v[52:55]
	v_mfma_f32_16x16x32_bf16 v[56:59], v[120:123], v[92:95], v[56:59]
	v_mfma_f32_16x16x32_bf16 v[60:63], v[124:127], v[92:95], v[60:63]
	ds_read_b128 v[80:83], v253 offset:0
	ds_read_b128 v[112:115], v255 offset:32768
	ds_read_b128 v[116:119], v255 offset:34816
	ds_read_b128 v[120:123], v255 offset:36864
	ds_read_b128 v[124:127], v255 offset:38912
	ds_read_b128 v[84:87], v253 offset:2048
	ds_read_b128 v[88:91], v253 offset:4096
	ds_read_b128 v[92:95], v253 offset:6144
	s_waitcnt lgkmcnt(14)
	v_mfma_f32_16x16x32_bf16 v[0:3], v[96:99], v[64:67], v[0:3]
	s_waitcnt lgkmcnt(13)
	v_mfma_f32_16x16x32_bf16 v[4:7], v[100:103], v[64:67], v[4:7]
	s_waitcnt lgkmcnt(12)
	v_mfma_f32_16x16x32_bf16 v[8:11], v[104:107], v[64:67], v[8:11]
	s_waitcnt lgkmcnt(11)
	v_mfma_f32_16x16x32_bf16 v[12:15], v[108:111], v[64:67], v[12:15]
	s_waitcnt lgkmcnt(10)
	v_mfma_f32_16x16x32_bf16 v[16:19], v[96:99], v[68:71], v[16:19]
	v_mfma_f32_16x16x32_bf16 v[20:23], v[100:103], v[68:71], v[20:23]
	v_mfma_f32_16x16x32_bf16 v[24:27], v[104:107], v[68:71], v[24:27]
	v_mfma_f32_16x16x32_bf16 v[28:31], v[108:111], v[68:71], v[28:31]
	s_waitcnt lgkmcnt(0)
	s_barrier
	v_mfma_f32_16x16x32_bf16 v[32:35], v[96:99], v[72:75], v[32:35]
	v_mfma_f32_16x16x32_bf16 v[36:39], v[100:103], v[72:75], v[36:39]
	v_mfma_f32_16x16x32_bf16 v[40:43], v[104:107], v[72:75], v[40:43]
	v_mfma_f32_16x16x32_bf16 v[44:47], v[108:111], v[72:75], v[44:47]
	v_mfma_f32_16x16x32_bf16 v[48:51], v[96:99], v[76:79], v[48:51]
	v_mfma_f32_16x16x32_bf16 v[52:55], v[100:103], v[76:79], v[52:55]
	v_mfma_f32_16x16x32_bf16 v[56:59], v[104:107], v[76:79], v[56:59]
	v_mfma_f32_16x16x32_bf16 v[60:63], v[108:111], v[76:79], v[60:63]
	s_waitcnt vmcnt(0)
	s_barrier
	ds_read_b128 v[64:67], v252 offset:16384
	ds_read_b128 v[96:99], v254 offset:49152
	ds_read_b128 v[100:103], v254 offset:51200
	ds_read_b128 v[104:107], v254 offset:53248
	ds_read_b128 v[108:111], v254 offset:55296
	ds_read_b128 v[68:71], v252 offset:18432
	ds_read_b128 v[72:75], v252 offset:20480
	ds_read_b128 v[76:79], v252 offset:22528
	v_mfma_f32_16x16x32_bf16 v[0:3], v[112:115], v[80:83], v[0:3]
	v_mfma_f32_16x16x32_bf16 v[4:7], v[116:119], v[80:83], v[4:7]
	v_mfma_f32_16x16x32_bf16 v[8:11], v[120:123], v[80:83], v[8:11]
	v_mfma_f32_16x16x32_bf16 v[12:15], v[124:127], v[80:83], v[12:15]
	v_mfma_f32_16x16x32_bf16 v[16:19], v[112:115], v[84:87], v[16:19]
	v_mfma_f32_16x16x32_bf16 v[20:23], v[116:119], v[84:87], v[20:23]
	v_mfma_f32_16x16x32_bf16 v[24:27], v[120:123], v[84:87], v[24:27]
	v_mfma_f32_16x16x32_bf16 v[28:31], v[124:127], v[84:87], v[28:31]
	v_mfma_f32_16x16x32_bf16 v[32:35], v[112:115], v[88:91], v[32:35]
	v_mfma_f32_16x16x32_bf16 v[36:39], v[116:119], v[88:91], v[36:39]
	v_mfma_f32_16x16x32_bf16 v[40:43], v[120:123], v[88:91], v[40:43]
	v_mfma_f32_16x16x32_bf16 v[44:47], v[124:127], v[88:91], v[44:47]
	v_mfma_f32_16x16x32_bf16 v[48:51], v[112:115], v[92:95], v[48:51]
	v_mfma_f32_16x16x32_bf16 v[52:55], v[116:119], v[92:95], v[52:55]
	v_mfma_f32_16x16x32_bf16 v[56:59], v[120:123], v[92:95], v[56:59]
	v_mfma_f32_16x16x32_bf16 v[60:63], v[124:127], v[92:95], v[60:63]
	ds_read_b128 v[80:83], v253 offset:16384
	ds_read_b128 v[112:115], v255 offset:49152
	ds_read_b128 v[116:119], v255 offset:51200
	ds_read_b128 v[120:123], v255 offset:53248
	ds_read_b128 v[124:127], v255 offset:55296
	ds_read_b128 v[84:87], v253 offset:18432
	ds_read_b128 v[88:91], v253 offset:20480
	ds_read_b128 v[92:95], v253 offset:22528
	s_waitcnt lgkmcnt(14)
	v_mfma_f32_16x16x32_bf16 v[0:3], v[96:99], v[64:67], v[0:3]
	s_waitcnt lgkmcnt(13)
	v_mfma_f32_16x16x32_bf16 v[4:7], v[100:103], v[64:67], v[4:7]
	s_waitcnt lgkmcnt(12)
	v_mfma_f32_16x16x32_bf16 v[8:11], v[104:107], v[64:67], v[8:11]
	s_waitcnt lgkmcnt(11)
	v_mfma_f32_16x16x32_bf16 v[12:15], v[108:111], v[64:67], v[12:15]
	s_waitcnt lgkmcnt(10)
	v_mfma_f32_16x16x32_bf16 v[16:19], v[96:99], v[68:71], v[16:19]
	v_mfma_f32_16x16x32_bf16 v[20:23], v[100:103], v[68:71], v[20:23]
	v_mfma_f32_16x16x32_bf16 v[24:27], v[104:107], v[68:71], v[24:27]
	v_mfma_f32_16x16x32_bf16 v[28:31], v[108:111], v[68:71], v[28:31]
	s_waitcnt lgkmcnt(0)
	s_barrier
	v_mfma_f32_16x16x32_bf16 v[32:35], v[96:99], v[72:75], v[32:35]
	v_mfma_f32_16x16x32_bf16 v[36:39], v[100:103], v[72:75], v[36:39]
	v_mfma_f32_16x16x32_bf16 v[40:43], v[104:107], v[72:75], v[40:43]
	v_mfma_f32_16x16x32_bf16 v[44:47], v[108:111], v[72:75], v[44:47]
	v_mfma_f32_16x16x32_bf16 v[48:51], v[96:99], v[76:79], v[48:51]
	v_mfma_f32_16x16x32_bf16 v[52:55], v[100:103], v[76:79], v[52:55]
	v_mfma_f32_16x16x32_bf16 v[56:59], v[104:107], v[76:79], v[56:59]
	v_mfma_f32_16x16x32_bf16 v[60:63], v[108:111], v[76:79], v[60:63]
	v_mfma_f32_16x16x32_bf16 v[0:3], v[112:115], v[80:83], v[0:3]
	v_mfma_f32_16x16x32_bf16 v[4:7], v[116:119], v[80:83], v[4:7]
	v_mfma_f32_16x16x32_bf16 v[8:11], v[120:123], v[80:83], v[8:11]
	v_mfma_f32_16x16x32_bf16 v[12:15], v[124:127], v[80:83], v[12:15]
	v_mfma_f32_16x16x32_bf16 v[16:19], v[112:115], v[84:87], v[16:19]
	v_mfma_f32_16x16x32_bf16 v[20:23], v[116:119], v[84:87], v[20:23]
	v_mfma_f32_16x16x32_bf16 v[24:27], v[120:123], v[84:87], v[24:27]
	v_mfma_f32_16x16x32_bf16 v[28:31], v[124:127], v[84:87], v[28:31]
	v_mfma_f32_16x16x32_bf16 v[32:35], v[112:115], v[88:91], v[32:35]
	v_mfma_f32_16x16x32_bf16 v[36:39], v[116:119], v[88:91], v[36:39]
	v_mfma_f32_16x16x32_bf16 v[40:43], v[120:123], v[88:91], v[40:43]
	v_mfma_f32_16x16x32_bf16 v[44:47], v[124:127], v[88:91], v[44:47]
	v_mfma_f32_16x16x32_bf16 v[48:51], v[112:115], v[92:95], v[48:51]
	v_mfma_f32_16x16x32_bf16 v[52:55], v[116:119], v[92:95], v[52:55]
	v_mfma_f32_16x16x32_bf16 v[56:59], v[120:123], v[92:95], v[56:59]
	v_mfma_f32_16x16x32_bf16 v[60:63], v[124:127], v[92:95], v[60:63]
	s_nop 7
	s_nop 1
	v_mul_f32_e32 v130, 0xbfb8aa3b, v0
	v_mul_f32_e32 v131, 0xbfb8aa3b, v1
	v_mul_f32_e32 v132, 0xbfb8aa3b, v2
	v_mul_f32_e32 v133, 0xbfb8aa3b, v3
	v_mul_f32_e32 v134, 0xbfb8aa3b, v4
	v_mul_f32_e32 v135, 0xbfb8aa3b, v5
	v_mul_f32_e32 v136, 0xbfb8aa3b, v6
	v_mul_f32_e32 v137, 0xbfb8aa3b, v7
	v_exp_f32_e32 v130, v130
	v_exp_f32_e32 v131, v131
	v_exp_f32_e32 v132, v132
	v_exp_f32_e32 v133, v133
	v_exp_f32_e32 v134, v134
	v_exp_f32_e32 v135, v135
	v_exp_f32_e32 v136, v136
	v_exp_f32_e32 v137, v137
	v_add_f32_e32 v130, 1.0, v130
	v_add_f32_e32 v131, 1.0, v131
	v_add_f32_e32 v132, 1.0, v132
	v_add_f32_e32 v133, 1.0, v133
	v_add_f32_e32 v134, 1.0, v134
	v_add_f32_e32 v135, 1.0, v135
	v_add_f32_e32 v136, 1.0, v136
	v_add_f32_e32 v137, 1.0, v137
	v_rcp_f32_e32 v130, v130
	v_rcp_f32_e32 v131, v131
	v_rcp_f32_e32 v132, v132
	v_rcp_f32_e32 v133, v133
	v_rcp_f32_e32 v134, v134
	v_rcp_f32_e32 v135, v135
	v_rcp_f32_e32 v136, v136
	v_rcp_f32_e32 v137, v137
	v_mul_f32_e32 v130, v0, v130
	v_mul_f32_e32 v131, v1, v131
	v_mul_f32_e32 v132, v2, v132
	v_mul_f32_e32 v133, v3, v133
	v_mul_f32_e32 v134, v4, v134
	v_mul_f32_e32 v135, v5, v135
	v_mul_f32_e32 v136, v6, v136
	v_mul_f32_e32 v137, v7, v137
	v_mul_f32_e32 v130, v8, v130
	v_mul_f32_e32 v131, v9, v131
	v_mul_f32_e32 v132, v10, v132
	v_mul_f32_e32 v133, v11, v133
	v_mul_f32_e32 v134, v12, v134
	v_mul_f32_e32 v135, v13, v135
	v_mul_f32_e32 v136, v14, v136
	v_mul_f32_e32 v137, v15, v137
	v_cvt_pk_bf16_f32 v0, v130, v131
	v_cvt_pk_bf16_f32 v1, v132, v133
	v_cvt_pk_bf16_f32 v2, v134, v135
	v_cvt_pk_bf16_f32 v3, v136, v137
	ds_write_b64 v245, v[0:1] offset:0
	ds_write_b64 v245, v[2:3] offset:32
	v_mul_f32_e32 v130, 0xbfb8aa3b, v16
	v_mul_f32_e32 v131, 0xbfb8aa3b, v17
	v_mul_f32_e32 v132, 0xbfb8aa3b, v18
	v_mul_f32_e32 v133, 0xbfb8aa3b, v19
	v_mul_f32_e32 v134, 0xbfb8aa3b, v20
	v_mul_f32_e32 v135, 0xbfb8aa3b, v21
	v_mul_f32_e32 v136, 0xbfb8aa3b, v22
	v_mul_f32_e32 v137, 0xbfb8aa3b, v23
	v_exp_f32_e32 v130, v130
	v_exp_f32_e32 v131, v131
	v_exp_f32_e32 v132, v132
	v_exp_f32_e32 v133, v133
	v_exp_f32_e32 v134, v134
	v_exp_f32_e32 v135, v135
	v_exp_f32_e32 v136, v136
	v_exp_f32_e32 v137, v137
	v_add_f32_e32 v130, 1.0, v130
	v_add_f32_e32 v131, 1.0, v131
	v_add_f32_e32 v132, 1.0, v132
	v_add_f32_e32 v133, 1.0, v133
	v_add_f32_e32 v134, 1.0, v134
	v_add_f32_e32 v135, 1.0, v135
	v_add_f32_e32 v136, 1.0, v136
	v_add_f32_e32 v137, 1.0, v137
	v_rcp_f32_e32 v130, v130
	v_rcp_f32_e32 v131, v131
	v_rcp_f32_e32 v132, v132
	v_rcp_f32_e32 v133, v133
	v_rcp_f32_e32 v134, v134
	v_rcp_f32_e32 v135, v135
	v_rcp_f32_e32 v136, v136
	v_rcp_f32_e32 v137, v137
	v_mul_f32_e32 v130, v16, v130
	v_mul_f32_e32 v131, v17, v131
	v_mul_f32_e32 v132, v18, v132
	v_mul_f32_e32 v133, v19, v133
	v_mul_f32_e32 v134, v20, v134
	v_mul_f32_e32 v135, v21, v135
	v_mul_f32_e32 v136, v22, v136
	v_mul_f32_e32 v137, v23, v137
	v_mul_f32_e32 v130, v24, v130
	v_mul_f32_e32 v131, v25, v131
	v_mul_f32_e32 v132, v26, v132
	v_mul_f32_e32 v133, v27, v133
	v_mul_f32_e32 v134, v28, v134
	v_mul_f32_e32 v135, v29, v135
	v_mul_f32_e32 v136, v30, v136
	v_mul_f32_e32 v137, v31, v137
	v_cvt_pk_bf16_f32 v16, v130, v131
	v_cvt_pk_bf16_f32 v17, v132, v133
	v_cvt_pk_bf16_f32 v18, v134, v135
	v_cvt_pk_bf16_f32 v19, v136, v137
	ds_write_b64 v245, v[16:17] offset:1280
	ds_write_b64 v245, v[18:19] offset:1312
	v_mul_f32_e32 v130, 0xbfb8aa3b, v32
	v_mul_f32_e32 v131, 0xbfb8aa3b, v33
	v_mul_f32_e32 v132, 0xbfb8aa3b, v34
	v_mul_f32_e32 v133, 0xbfb8aa3b, v35
	v_mul_f32_e32 v134, 0xbfb8aa3b, v36
	v_mul_f32_e32 v135, 0xbfb8aa3b, v37
	v_mul_f32_e32 v136, 0xbfb8aa3b, v38
	v_mul_f32_e32 v137, 0xbfb8aa3b, v39
	v_exp_f32_e32 v130, v130
	v_exp_f32_e32 v131, v131
	v_exp_f32_e32 v132, v132
	v_exp_f32_e32 v133, v133
	v_exp_f32_e32 v134, v134
	v_exp_f32_e32 v135, v135
	v_exp_f32_e32 v136, v136
	v_exp_f32_e32 v137, v137
	v_add_f32_e32 v130, 1.0, v130
	v_add_f32_e32 v131, 1.0, v131
	v_add_f32_e32 v132, 1.0, v132
	v_add_f32_e32 v133, 1.0, v133
	v_add_f32_e32 v134, 1.0, v134
	v_add_f32_e32 v135, 1.0, v135
	v_add_f32_e32 v136, 1.0, v136
	v_add_f32_e32 v137, 1.0, v137
	v_rcp_f32_e32 v130, v130
	v_rcp_f32_e32 v131, v131
	v_rcp_f32_e32 v132, v132
	v_rcp_f32_e32 v133, v133
	v_rcp_f32_e32 v134, v134
	v_rcp_f32_e32 v135, v135
	v_rcp_f32_e32 v136, v136
	v_rcp_f32_e32 v137, v137
	v_mul_f32_e32 v130, v32, v130
	v_mul_f32_e32 v131, v33, v131
	v_mul_f32_e32 v132, v34, v132
	v_mul_f32_e32 v133, v35, v133
	v_mul_f32_e32 v134, v36, v134
	v_mul_f32_e32 v135, v37, v135
	v_mul_f32_e32 v136, v38, v136
	v_mul_f32_e32 v137, v39, v137
	v_mul_f32_e32 v130, v40, v130
	v_mul_f32_e32 v131, v41, v131
	v_mul_f32_e32 v132, v42, v132
	v_mul_f32_e32 v133, v43, v133
	v_mul_f32_e32 v134, v44, v134
	v_mul_f32_e32 v135, v45, v135
	v_mul_f32_e32 v136, v46, v136
	v_mul_f32_e32 v137, v47, v137
	v_cvt_pk_bf16_f32 v32, v130, v131
	v_cvt_pk_bf16_f32 v33, v132, v133
	v_cvt_pk_bf16_f32 v34, v134, v135
	v_cvt_pk_bf16_f32 v35, v136, v137
	ds_write_b64 v245, v[32:33] offset:2560
	ds_write_b64 v245, v[34:35] offset:2592
	v_mul_f32_e32 v130, 0xbfb8aa3b, v48
	v_mul_f32_e32 v131, 0xbfb8aa3b, v49
	v_mul_f32_e32 v132, 0xbfb8aa3b, v50
	v_mul_f32_e32 v133, 0xbfb8aa3b, v51
	v_mul_f32_e32 v134, 0xbfb8aa3b, v52
	v_mul_f32_e32 v135, 0xbfb8aa3b, v53
	v_mul_f32_e32 v136, 0xbfb8aa3b, v54
	v_mul_f32_e32 v137, 0xbfb8aa3b, v55
	v_exp_f32_e32 v130, v130
	v_exp_f32_e32 v131, v131
	v_exp_f32_e32 v132, v132
	v_exp_f32_e32 v133, v133
	v_exp_f32_e32 v134, v134
	v_exp_f32_e32 v135, v135
	v_exp_f32_e32 v136, v136
	v_exp_f32_e32 v137, v137
	v_add_f32_e32 v130, 1.0, v130
	v_add_f32_e32 v131, 1.0, v131
	v_add_f32_e32 v132, 1.0, v132
	v_add_f32_e32 v133, 1.0, v133
	v_add_f32_e32 v134, 1.0, v134
	v_add_f32_e32 v135, 1.0, v135
	v_add_f32_e32 v136, 1.0, v136
	v_add_f32_e32 v137, 1.0, v137
	v_rcp_f32_e32 v130, v130
	v_rcp_f32_e32 v131, v131
	v_rcp_f32_e32 v132, v132
	v_rcp_f32_e32 v133, v133
	v_rcp_f32_e32 v134, v134
	v_rcp_f32_e32 v135, v135
	v_rcp_f32_e32 v136, v136
	v_rcp_f32_e32 v137, v137
	v_mul_f32_e32 v130, v48, v130
	v_mul_f32_e32 v131, v49, v131
	v_mul_f32_e32 v132, v50, v132
	v_mul_f32_e32 v133, v51, v133
	v_mul_f32_e32 v134, v52, v134
	v_mul_f32_e32 v135, v53, v135
	v_mul_f32_e32 v136, v54, v136
	v_mul_f32_e32 v137, v55, v137
	v_mul_f32_e32 v130, v56, v130
	v_mul_f32_e32 v131, v57, v131
	v_mul_f32_e32 v132, v58, v132
	v_mul_f32_e32 v133, v59, v133
	v_mul_f32_e32 v134, v60, v134
	v_mul_f32_e32 v135, v61, v135
	v_mul_f32_e32 v136, v62, v136
	v_mul_f32_e32 v137, v63, v137
	v_cvt_pk_bf16_f32 v48, v130, v131
	v_cvt_pk_bf16_f32 v49, v132, v133
	v_cvt_pk_bf16_f32 v50, v134, v135
	v_cvt_pk_bf16_f32 v51, v136, v137
	ds_write_b64 v245, v[48:49] offset:3840
	ds_write_b64 v245, v[50:51] offset:3872
	s_waitcnt lgkmcnt(0)
	ds_read_b128 v[138:141], v246 offset:0
	ds_read_b128 v[142:145], v246 offset:1280
	ds_read_b128 v[146:149], v246 offset:2560
	ds_read_b128 v[150:153], v246 offset:3840
	s_mov_b64 s[18:19], s[20:21]
	s_waitcnt lgkmcnt(3)
	global_store_dwordx4 v239, v[138:141], s[18:19]
	s_add_u32 s18, s18, 0x16000
	s_addc_u32 s19, s19, 0
	s_waitcnt lgkmcnt(2)
	global_store_dwordx4 v239, v[142:145], s[18:19]
	s_add_u32 s18, s18, 0x16000
	s_addc_u32 s19, s19, 0
	s_waitcnt lgkmcnt(1)
	global_store_dwordx4 v239, v[146:149], s[18:19]
	s_add_u32 s18, s18, 0x16000
	s_addc_u32 s19, s19, 0
	s_waitcnt lgkmcnt(0)
	global_store_dwordx4 v239, v[150:153], s[18:19]
	s_barrier
	s_add_u32 s15, s15, s16
	s_branch .Lf8_tile
